# GEMM K-loops: redundant post-barrier lgkmcnt waits dropped; vmcnt/lgkmcnt wait pairs merged into one instruction
# speedup vs baseline: 1.0033x; 1.0006x over previous
.Lgprio0:
.LBB0_169:
	s_add_u32 s42, s40, 0xfff80080
	s_addc_u32 s43, s41, -1
	s_add_i32 s52, 0, 0x10000
	s_cmp_eq_u32 s51, 28
	s_cselect_b32 s45, s13, s43
	s_cselect_b32 s44, s47, s42
	s_cselect_b32 s43, s11, s50
	s_cselect_b32 s42, s48, s49
	s_add_i32 s54, 0, 0x14000
	v_add_u32_e32 v142, s52, v175
	v_add_u32_e32 v154, s54, v175
	ds_read_b128 v[130:133], v142
	ds_read_b128 v[134:137], v142 offset:1024
	ds_read_b128 v[138:141], v142 offset:2048
	ds_read_b128 v[142:145], v142 offset:3072
	ds_read_b128 v[170:173], v154
	ds_read_b128 v[184:187], v154 offset:1024
	ds_read_b128 v[188:191], v154 offset:2048
	ds_read_b128 v[192:195], v154 offset:3072
	s_add_i32 m0, s14, 0xc000
	ds_read_b128 v[196:199], v183
	ds_read_b128 v[200:203], v183 offset:1024
	ds_read_b128 v[210:213], v183 offset:2048
	ds_read_b128 v[214:217], v183 offset:3072
	ds_read_b128 v[218:221], v183 offset:4096
	ds_read_b128 v[222:225], v183 offset:5120
	ds_read_b128 v[226:229], v183 offset:6144
	ds_read_b128 v[230:233], v183 offset:7168
	global_load_lds_dwordx4 v166, s[40:41]
	s_add_i32 m0, s14, 0xe000
	s_nop 0
	global_load_lds_dwordx4 v168, s[40:41]
	s_waitcnt vmcnt(8) lgkmcnt(0)
	s_barrier
	v_mfma_f32_16x16x32_bf16 v[126:129], v[130:133], v[196:199], v[126:129]
	v_mfma_f32_16x16x32_bf16 v[122:125], v[138:141], v[196:199], v[122:125]
	v_mfma_f32_16x16x32_bf16 v[118:121], v[130:133], v[210:213], v[118:121]
	v_mfma_f32_16x16x32_bf16 v[110:113], v[138:141], v[210:213], v[110:113]
	v_mfma_f32_16x16x32_bf16 v[102:105], v[130:133], v[218:221], v[102:105]
	v_mfma_f32_16x16x32_bf16 v[94:97], v[138:141], v[218:221], v[94:97]
	v_mfma_f32_16x16x32_bf16 v[86:89], v[130:133], v[226:229], v[86:89]
	v_mfma_f32_16x16x32_bf16 v[78:81], v[138:141], v[226:229], v[78:81]
	v_mfma_f32_16x16x32_bf16 v[126:129], v[134:137], v[200:203], v[126:129]
	v_mfma_f32_16x16x32_bf16 v[122:125], v[142:145], v[200:203], v[122:125]
	v_mfma_f32_16x16x32_bf16 v[118:121], v[134:137], v[214:217], v[118:121]
	v_mfma_f32_16x16x32_bf16 v[110:113], v[142:145], v[214:217], v[110:113]
	v_mfma_f32_16x16x32_bf16 v[102:105], v[134:137], v[222:225], v[102:105]
	v_mfma_f32_16x16x32_bf16 v[94:97], v[142:145], v[222:225], v[94:97]
	v_mfma_f32_16x16x32_bf16 v[86:89], v[134:137], v[230:233], v[86:89]
	v_mfma_f32_16x16x32_bf16 v[78:81], v[142:145], v[230:233], v[78:81]
	v_mfma_f32_16x16x32_bf16 v[114:117], v[170:173], v[196:199], v[114:117]
	v_mfma_f32_16x16x32_bf16 v[106:109], v[188:191], v[196:199], v[106:109]
	v_mfma_f32_16x16x32_bf16 v[98:101], v[170:173], v[210:213], v[98:101]
	v_mfma_f32_16x16x32_bf16 v[90:93], v[188:191], v[210:213], v[90:93]
	v_mfma_f32_16x16x32_bf16 v[82:85], v[170:173], v[218:221], v[82:85]
	v_mfma_f32_16x16x32_bf16 v[74:77], v[188:191], v[218:221], v[74:77]
	v_mfma_f32_16x16x32_bf16 v[70:73], v[170:173], v[226:229], v[70:73]
	v_mfma_f32_16x16x32_bf16 v[66:69], v[188:191], v[226:229], v[66:69]
	v_mfma_f32_16x16x32_bf16 v[114:117], v[184:187], v[200:203], v[114:117]
	v_mfma_f32_16x16x32_bf16 v[106:109], v[192:195], v[200:203], v[106:109]
	v_mfma_f32_16x16x32_bf16 v[98:101], v[184:187], v[214:217], v[98:101]
	v_mfma_f32_16x16x32_bf16 v[90:93], v[192:195], v[214:217], v[90:93]
	v_mfma_f32_16x16x32_bf16 v[82:85], v[184:187], v[222:225], v[82:85]
	v_mfma_f32_16x16x32_bf16 v[74:77], v[192:195], v[222:225], v[74:77]
	v_mfma_f32_16x16x32_bf16 v[70:73], v[184:187], v[230:233], v[70:73]
	v_mfma_f32_16x16x32_bf16 v[66:69], v[192:195], v[230:233], v[66:69]
	s_barrier
	s_add_i32 s52, s52, s5
	v_lshl_add_u64 v[154:155], s[42:43], 0, v[162:163]
	s_mov_b32 m0, s52
	ds_read_b128 v[196:199], v183 offset:16384
	ds_read_b128 v[200:203], v183 offset:17408
	ds_read_b128 v[210:213], v183 offset:18432
	ds_read_b128 v[214:217], v183 offset:19456
	ds_read_b128 v[218:221], v183 offset:20480
	ds_read_b128 v[222:225], v183 offset:21504
	ds_read_b128 v[226:229], v183 offset:22528
	ds_read_b128 v[230:233], v183 offset:23552
	global_load_lds_dwordx4 v[154:155], off
	s_add_i32 m0, s52, 0x2000
	s_add_u32 s52, s42, 0x80000
	v_lshl_add_u64 v[156:157], s[42:43], 0, v[158:159]
	s_addc_u32 s53, s43, 0
	s_add_i32 s54, s54, s5
	global_load_lds_dwordx4 v[156:157], off
	s_mov_b32 m0, s54
	v_lshl_add_u64 v[180:181], s[44:45], 0, v[160:161]
	global_load_lds_dwordx4 v162, s[52:53]
	s_add_i32 m0, s54, 0x2000
	s_nop 0
	global_load_lds_dwordx4 v158, s[52:53]
	v_lshl_add_u64 v[176:177], s[44:45], 0, v[164:165]
	s_mov_b32 m0, s14
	s_nop 0
	global_load_lds_dwordx4 v[176:177], off
	s_mov_b32 m0, s15
	s_nop 0
	global_load_lds_dwordx4 v[180:181], off
	s_waitcnt vmcnt(8) lgkmcnt(0)
	s_barrier
	v_mfma_f32_16x16x32_bf16 v[62:65], v[130:133], v[196:199], v[62:65]
	v_mfma_f32_16x16x32_bf16 v[58:61], v[138:141], v[196:199], v[58:61]
	v_mfma_f32_16x16x32_bf16 v[54:57], v[130:133], v[210:213], v[54:57]
	v_mfma_f32_16x16x32_bf16 v[46:49], v[138:141], v[210:213], v[46:49]
	v_mfma_f32_16x16x32_bf16 v[38:41], v[130:133], v[218:221], v[38:41]
	v_mfma_f32_16x16x32_bf16 v[30:33], v[138:141], v[218:221], v[30:33]
	v_mfma_f32_16x16x32_bf16 v[22:25], v[130:133], v[226:229], v[22:25]
	v_mfma_f32_16x16x32_bf16 v[14:17], v[138:141], v[226:229], v[14:17]
	v_mfma_f32_16x16x32_bf16 v[62:65], v[134:137], v[200:203], v[62:65]
	v_mfma_f32_16x16x32_bf16 v[58:61], v[142:145], v[200:203], v[58:61]
	v_mfma_f32_16x16x32_bf16 v[54:57], v[134:137], v[214:217], v[54:57]
	v_mfma_f32_16x16x32_bf16 v[46:49], v[142:145], v[214:217], v[46:49]
	v_mfma_f32_16x16x32_bf16 v[38:41], v[134:137], v[222:225], v[38:41]
	v_mfma_f32_16x16x32_bf16 v[30:33], v[142:145], v[222:225], v[30:33]
	v_mfma_f32_16x16x32_bf16 v[22:25], v[134:137], v[230:233], v[22:25]
	v_mfma_f32_16x16x32_bf16 v[14:17], v[142:145], v[230:233], v[14:17]
	v_mfma_f32_16x16x32_bf16 v[50:53], v[170:173], v[196:199], v[50:53]
	v_mfma_f32_16x16x32_bf16 v[42:45], v[188:191], v[196:199], v[42:45]
	v_mfma_f32_16x16x32_bf16 v[34:37], v[170:173], v[210:213], v[34:37]
	v_mfma_f32_16x16x32_bf16 v[26:29], v[188:191], v[210:213], v[26:29]
	v_mfma_f32_16x16x32_bf16 v[18:21], v[170:173], v[218:221], v[18:21]
	v_mfma_f32_16x16x32_bf16 v[10:13], v[188:191], v[218:221], v[10:13]
	v_mfma_f32_16x16x32_bf16 v[6:9], v[170:173], v[226:229], v[6:9]
	v_mfma_f32_16x16x32_bf16 v[2:5], v[188:191], v[226:229], v[2:5]
	v_mfma_f32_16x16x32_bf16 v[50:53], v[184:187], v[200:203], v[50:53]
	v_mfma_f32_16x16x32_bf16 v[42:45], v[192:195], v[200:203], v[42:45]
	v_mfma_f32_16x16x32_bf16 v[34:37], v[184:187], v[214:217], v[34:37]
	v_mfma_f32_16x16x32_bf16 v[26:29], v[192:195], v[214:217], v[26:29]
	v_mfma_f32_16x16x32_bf16 v[18:21], v[184:187], v[222:225], v[18:21]
	v_mfma_f32_16x16x32_bf16 v[10:13], v[192:195], v[222:225], v[10:13]
	v_mfma_f32_16x16x32_bf16 v[6:9], v[184:187], v[230:233], v[6:9]
	v_mfma_f32_16x16x32_bf16 v[2:5], v[192:195], v[230:233], v[2:5]
	s_barrier
	s_add_i32 s52, 0, 0x18000
	s_add_i32 s53, 0, 0x1c000
	v_add_u32_e32 v142, s52, v175
	v_add_u32_e32 v174, s53, v175
	ds_read_b128 v[130:133], v142
	ds_read_b128 v[134:137], v142 offset:1024
	ds_read_b128 v[138:141], v142 offset:2048
	ds_read_b128 v[142:145], v142 offset:3072
	ds_read_b128 v[170:173], v174
	ds_read_b128 v[184:187], v174 offset:1024
	ds_read_b128 v[188:191], v174 offset:2048
	ds_read_b128 v[192:195], v174 offset:3072
	s_add_u32 s44, s44, 0x80000
	s_addc_u32 s45, s45, 0
	s_mov_b32 m0, s16
	ds_read_b128 v[196:199], v183 offset:32768
	ds_read_b128 v[200:203], v183 offset:33792
	ds_read_b128 v[210:213], v183 offset:34816
	ds_read_b128 v[214:217], v183 offset:35840
	ds_read_b128 v[218:221], v183 offset:36864
	ds_read_b128 v[222:225], v183 offset:37888
	ds_read_b128 v[226:229], v183 offset:38912
	ds_read_b128 v[230:233], v183 offset:39936
	global_load_lds_dwordx4 v164, s[44:45]
	s_mov_b32 m0, s18
	s_nop 0
	global_load_lds_dwordx4 v160, s[44:45]
	s_waitcnt vmcnt(8) lgkmcnt(0)
	s_barrier
	v_mfma_f32_16x16x32_bf16 v[126:129], v[130:133], v[196:199], v[126:129]
	v_mfma_f32_16x16x32_bf16 v[122:125], v[138:141], v[196:199], v[122:125]
	v_mfma_f32_16x16x32_bf16 v[118:121], v[130:133], v[210:213], v[118:121]
	v_mfma_f32_16x16x32_bf16 v[110:113], v[138:141], v[210:213], v[110:113]
	v_mfma_f32_16x16x32_bf16 v[102:105], v[130:133], v[218:221], v[102:105]
	v_mfma_f32_16x16x32_bf16 v[94:97], v[138:141], v[218:221], v[94:97]
	v_mfma_f32_16x16x32_bf16 v[86:89], v[130:133], v[226:229], v[86:89]
	v_mfma_f32_16x16x32_bf16 v[78:81], v[138:141], v[226:229], v[78:81]
	v_mfma_f32_16x16x32_bf16 v[126:129], v[134:137], v[200:203], v[126:129]
	v_mfma_f32_16x16x32_bf16 v[122:125], v[142:145], v[200:203], v[122:125]
	v_mfma_f32_16x16x32_bf16 v[118:121], v[134:137], v[214:217], v[118:121]
	v_mfma_f32_16x16x32_bf16 v[110:113], v[142:145], v[214:217], v[110:113]
	v_mfma_f32_16x16x32_bf16 v[102:105], v[134:137], v[222:225], v[102:105]
	v_mfma_f32_16x16x32_bf16 v[94:97], v[142:145], v[222:225], v[94:97]
	v_mfma_f32_16x16x32_bf16 v[86:89], v[134:137], v[230:233], v[86:89]
	v_mfma_f32_16x16x32_bf16 v[78:81], v[142:145], v[230:233], v[78:81]
	v_mfma_f32_16x16x32_bf16 v[114:117], v[170:173], v[196:199], v[114:117]
	v_mfma_f32_16x16x32_bf16 v[106:109], v[188:191], v[196:199], v[106:109]
	v_mfma_f32_16x16x32_bf16 v[98:101], v[170:173], v[210:213], v[98:101]
	v_mfma_f32_16x16x32_bf16 v[90:93], v[188:191], v[210:213], v[90:93]
	v_mfma_f32_16x16x32_bf16 v[82:85], v[170:173], v[218:221], v[82:85]
	v_mfma_f32_16x16x32_bf16 v[74:77], v[188:191], v[218:221], v[74:77]
	v_mfma_f32_16x16x32_bf16 v[70:73], v[170:173], v[226:229], v[70:73]
	v_mfma_f32_16x16x32_bf16 v[66:69], v[188:191], v[226:229], v[66:69]
	v_mfma_f32_16x16x32_bf16 v[114:117], v[184:187], v[200:203], v[114:117]
	v_mfma_f32_16x16x32_bf16 v[106:109], v[192:195], v[200:203], v[106:109]
	v_mfma_f32_16x16x32_bf16 v[98:101], v[184:187], v[214:217], v[98:101]
	v_mfma_f32_16x16x32_bf16 v[90:93], v[192:195], v[214:217], v[90:93]
	v_mfma_f32_16x16x32_bf16 v[82:85], v[184:187], v[222:225], v[82:85]
	v_mfma_f32_16x16x32_bf16 v[74:77], v[192:195], v[222:225], v[74:77]
	v_mfma_f32_16x16x32_bf16 v[70:73], v[184:187], v[230:233], v[70:73]
	v_mfma_f32_16x16x32_bf16 v[66:69], v[192:195], v[230:233], v[66:69]
	s_barrier
	s_add_i32 s44, s52, s5
	v_lshl_add_u64 v[154:155], v[154:155], 0, s[34:35]
	s_mov_b32 m0, s44
	ds_read_b128 v[196:199], v183 offset:49152
	ds_read_b128 v[200:203], v183 offset:50176
	ds_read_b128 v[210:213], v183 offset:51200
	ds_read_b128 v[214:217], v183 offset:52224
	ds_read_b128 v[218:221], v183 offset:53248
	ds_read_b128 v[222:225], v183 offset:54272
	ds_read_b128 v[226:229], v183 offset:55296
	ds_read_b128 v[230:233], v183 offset:56320
	global_load_lds_dwordx4 v[154:155], off
	s_add_i32 m0, s44, 0x2000
	s_add_u32 s42, s42, 0x80080
	v_lshl_add_u64 v[154:155], v[156:157], 0, s[34:35]
	s_addc_u32 s43, s43, 0
	s_add_i32 s44, s53, s5
	global_load_lds_dwordx4 v[154:155], off
	s_mov_b32 m0, s44
	s_nop 0
	global_load_lds_dwordx4 v162, s[42:43]
	s_add_i32 m0, s44, 0x2000
	s_nop 0
	global_load_lds_dwordx4 v158, s[42:43]
	v_lshl_add_u64 v[154:155], v[176:177], 0, s[34:35]
	s_mov_b32 m0, s19
	s_nop 0
	global_load_lds_dwordx4 v[154:155], off
	v_lshl_add_u64 v[154:155], v[180:181], 0, s[34:35]
	s_mov_b32 m0, s25
	s_nop 0
	global_load_lds_dwordx4 v[154:155], off
	s_waitcnt vmcnt(8) lgkmcnt(0)
	s_barrier
	v_mfma_f32_16x16x32_bf16 v[62:65], v[130:133], v[196:199], v[62:65]
	v_mfma_f32_16x16x32_bf16 v[58:61], v[138:141], v[196:199], v[58:61]
	v_mfma_f32_16x16x32_bf16 v[54:57], v[130:133], v[210:213], v[54:57]
	v_mfma_f32_16x16x32_bf16 v[46:49], v[138:141], v[210:213], v[46:49]
	v_mfma_f32_16x16x32_bf16 v[38:41], v[130:133], v[218:221], v[38:41]
	v_mfma_f32_16x16x32_bf16 v[30:33], v[138:141], v[218:221], v[30:33]
	v_mfma_f32_16x16x32_bf16 v[22:25], v[130:133], v[226:229], v[22:25]
	v_mfma_f32_16x16x32_bf16 v[14:17], v[138:141], v[226:229], v[14:17]
	v_mfma_f32_16x16x32_bf16 v[62:65], v[134:137], v[200:203], v[62:65]
	v_mfma_f32_16x16x32_bf16 v[58:61], v[142:145], v[200:203], v[58:61]
	v_mfma_f32_16x16x32_bf16 v[54:57], v[134:137], v[214:217], v[54:57]
	v_mfma_f32_16x16x32_bf16 v[46:49], v[142:145], v[214:217], v[46:49]
	v_mfma_f32_16x16x32_bf16 v[38:41], v[134:137], v[222:225], v[38:41]
	v_mfma_f32_16x16x32_bf16 v[30:33], v[142:145], v[222:225], v[30:33]
	v_mfma_f32_16x16x32_bf16 v[22:25], v[134:137], v[230:233], v[22:25]
	v_mfma_f32_16x16x32_bf16 v[14:17], v[142:145], v[230:233], v[14:17]
	v_mfma_f32_16x16x32_bf16 v[50:53], v[170:173], v[196:199], v[50:53]
	v_mfma_f32_16x16x32_bf16 v[42:45], v[188:191], v[196:199], v[42:45]
	v_mfma_f32_16x16x32_bf16 v[34:37], v[170:173], v[210:213], v[34:37]
	v_mfma_f32_16x16x32_bf16 v[26:29], v[188:191], v[210:213], v[26:29]
	v_mfma_f32_16x16x32_bf16 v[18:21], v[170:173], v[218:221], v[18:21]
	v_mfma_f32_16x16x32_bf16 v[10:13], v[188:191], v[218:221], v[10:13]
	v_mfma_f32_16x16x32_bf16 v[6:9], v[170:173], v[226:229], v[6:9]
	v_mfma_f32_16x16x32_bf16 v[2:5], v[188:191], v[226:229], v[2:5]
	v_mfma_f32_16x16x32_bf16 v[50:53], v[184:187], v[200:203], v[50:53]
	v_mfma_f32_16x16x32_bf16 v[42:45], v[192:195], v[200:203], v[42:45]
	v_mfma_f32_16x16x32_bf16 v[34:37], v[184:187], v[214:217], v[34:37]
	v_mfma_f32_16x16x32_bf16 v[26:29], v[192:195], v[214:217], v[26:29]
	v_mfma_f32_16x16x32_bf16 v[18:21], v[184:187], v[222:225], v[18:21]
	v_mfma_f32_16x16x32_bf16 v[10:13], v[192:195], v[222:225], v[10:13]
	v_mfma_f32_16x16x32_bf16 v[6:9], v[184:187], v[230:233], v[6:9]
	v_mfma_f32_16x16x32_bf16 v[2:5], v[192:195], v[230:233], v[2:5]
	s_barrier
	s_add_i32 s51, s51, 2
	s_add_u32 s40, s40, 0x100
	s_addc_u32 s41, s41, 0
	s_add_u32 s49, s49, 0x100
	s_addc_u32 s50, s50, 0
	s_cmp_gt_u32 s51, 29
	s_cbranch_scc0 .LBB0_169
	s_setprio 0
	s_and_b64 vcc, exec, s[8:9]
	s_cbranch_vccz .LBB0_172
	s_barrier

.Lgprio1:
.LBB0_516:
	s_add_u32 s46, s44, 0xfff80080
	s_addc_u32 s47, s45, -1
	s_add_i32 s58, 0, 0x10000
	s_cmp_eq_u32 s57, 28
	s_cselect_b32 s49, s21, s47
	s_cselect_b32 s48, s50, s46
	s_cselect_b32 s47, s13, s56
	s_cselect_b32 s46, s51, s55
	s_add_i32 s60, 0, 0x14000
	v_add_u32_e32 v102, s58, v172
	v_add_u32_e32 v175, s60, v172
	ds_read_b128 v[82:85], v102
	ds_read_b128 v[86:89], v102 offset:1024
	ds_read_b128 v[98:101], v102 offset:2048
	ds_read_b128 v[102:105], v102 offset:3072
	ds_read_b128 v[154:157], v175
	ds_read_b128 v[168:171], v175 offset:1024
	ds_read_b128 v[176:179], v175 offset:2048
	ds_read_b128 v[180:183], v175 offset:3072
	s_add_i32 m0, s14, 0xc000
	ds_read_b128 v[184:187], v174
	ds_read_b128 v[188:191], v174 offset:1024
	ds_read_b128 v[192:195], v174 offset:2048
	ds_read_b128 v[196:199], v174 offset:3072
	ds_read_b128 v[200:203], v174 offset:4096
	ds_read_b128 v[210:213], v174 offset:5120
	ds_read_b128 v[214:217], v174 offset:6144
	ds_read_b128 v[218:221], v174 offset:7168
	global_load_lds_dwordx4 v164, s[44:45]
	s_add_i32 m0, s14, 0xe000
	s_nop 0
	global_load_lds_dwordx4 v166, s[44:45]
	s_waitcnt vmcnt(8) lgkmcnt(0)
	s_barrier
	v_mfma_f32_16x16x32_bf16 v[142:145], v[82:85], v[184:187], v[142:145]
	v_mfma_f32_16x16x32_bf16 v[138:141], v[98:101], v[184:187], v[138:141]
	v_mfma_f32_16x16x32_bf16 v[126:129], v[82:85], v[192:195], v[126:129]
	v_mfma_f32_16x16x32_bf16 v[122:125], v[98:101], v[192:195], v[122:125]
	v_mfma_f32_16x16x32_bf16 v[110:113], v[82:85], v[200:203], v[110:113]
	v_mfma_f32_16x16x32_bf16 v[106:109], v[98:101], v[200:203], v[106:109]
	v_mfma_f32_16x16x32_bf16 v[78:81], v[82:85], v[214:217], v[78:81]
	v_mfma_f32_16x16x32_bf16 v[74:77], v[98:101], v[214:217], v[74:77]
	v_mfma_f32_16x16x32_bf16 v[142:145], v[86:89], v[188:191], v[142:145]
	v_mfma_f32_16x16x32_bf16 v[138:141], v[102:105], v[188:191], v[138:141]
	v_mfma_f32_16x16x32_bf16 v[126:129], v[86:89], v[196:199], v[126:129]
	v_mfma_f32_16x16x32_bf16 v[122:125], v[102:105], v[196:199], v[122:125]
	v_mfma_f32_16x16x32_bf16 v[110:113], v[86:89], v[210:213], v[110:113]
	v_mfma_f32_16x16x32_bf16 v[106:109], v[102:105], v[210:213], v[106:109]
	v_mfma_f32_16x16x32_bf16 v[78:81], v[86:89], v[218:221], v[78:81]
	v_mfma_f32_16x16x32_bf16 v[74:77], v[102:105], v[218:221], v[74:77]
	v_mfma_f32_16x16x32_bf16 v[134:137], v[154:157], v[184:187], v[134:137]
	v_mfma_f32_16x16x32_bf16 v[130:133], v[176:179], v[184:187], v[130:133]
	v_mfma_f32_16x16x32_bf16 v[118:121], v[154:157], v[192:195], v[118:121]
	v_mfma_f32_16x16x32_bf16 v[114:117], v[176:179], v[192:195], v[114:117]
	v_mfma_f32_16x16x32_bf16 v[94:97], v[154:157], v[200:203], v[94:97]
	v_mfma_f32_16x16x32_bf16 v[90:93], v[176:179], v[200:203], v[90:93]
	v_mfma_f32_16x16x32_bf16 v[70:73], v[154:157], v[214:217], v[70:73]
	v_mfma_f32_16x16x32_bf16 v[66:69], v[176:179], v[214:217], v[66:69]
	v_mfma_f32_16x16x32_bf16 v[134:137], v[168:171], v[188:191], v[134:137]
	v_mfma_f32_16x16x32_bf16 v[130:133], v[180:183], v[188:191], v[130:133]
	v_mfma_f32_16x16x32_bf16 v[118:121], v[168:171], v[196:199], v[118:121]
	v_mfma_f32_16x16x32_bf16 v[114:117], v[180:183], v[196:199], v[114:117]
	v_mfma_f32_16x16x32_bf16 v[94:97], v[168:171], v[210:213], v[94:97]
	v_mfma_f32_16x16x32_bf16 v[90:93], v[180:183], v[210:213], v[90:93]
	v_mfma_f32_16x16x32_bf16 v[70:73], v[168:171], v[218:221], v[70:73]
	v_mfma_f32_16x16x32_bf16 v[66:69], v[180:183], v[218:221], v[66:69]
	s_barrier
	s_add_i32 s58, s58, s5
	v_lshl_add_u64 v[222:223], s[46:47], 0, v[0:1]
	s_mov_b32 m0, s58
	ds_read_b128 v[184:187], v174 offset:16384
	ds_read_b128 v[188:191], v174 offset:17408
	ds_read_b128 v[192:195], v174 offset:18432
	ds_read_b128 v[196:199], v174 offset:19456
	ds_read_b128 v[200:203], v174 offset:20480
	ds_read_b128 v[210:213], v174 offset:21504
	ds_read_b128 v[214:217], v174 offset:22528
	ds_read_b128 v[218:221], v174 offset:23552
	global_load_lds_dwordx4 v[222:223], off
	s_add_i32 m0, s58, 0x2000
	s_add_u32 s58, s46, 0x80000
	v_lshl_add_u64 v[224:225], s[46:47], 0, v[158:159]
	s_addc_u32 s59, s47, 0
	s_add_i32 s60, s60, s5
	global_load_lds_dwordx4 v[224:225], off
	s_mov_b32 m0, s60
	v_lshl_add_u64 v[228:229], s[48:49], 0, v[160:161]
	global_load_lds_dwordx4 v0, s[58:59]
	s_add_i32 m0, s60, 0x2000
	s_nop 0
	global_load_lds_dwordx4 v158, s[58:59]
	v_lshl_add_u64 v[226:227], s[48:49], 0, v[162:163]
	s_mov_b32 m0, s14
	s_nop 0
	global_load_lds_dwordx4 v[226:227], off
	s_mov_b32 m0, s15
	s_nop 0
	global_load_lds_dwordx4 v[228:229], off
	s_waitcnt vmcnt(8) lgkmcnt(0)
	s_barrier
	v_mfma_f32_16x16x32_bf16 v[62:65], v[82:85], v[184:187], v[62:65]
	v_mfma_f32_16x16x32_bf16 v[58:61], v[98:101], v[184:187], v[58:61]
	v_mfma_f32_16x16x32_bf16 v[46:49], v[82:85], v[192:195], v[46:49]
	v_mfma_f32_16x16x32_bf16 v[42:45], v[98:101], v[192:195], v[42:45]
	v_mfma_f32_16x16x32_bf16 v[30:33], v[82:85], v[200:203], v[30:33]
	v_mfma_f32_16x16x32_bf16 v[26:29], v[98:101], v[200:203], v[26:29]
	v_mfma_f32_16x16x32_bf16 v[14:17], v[82:85], v[214:217], v[14:17]
	v_mfma_f32_16x16x32_bf16 v[10:13], v[98:101], v[214:217], v[10:13]
	v_mfma_f32_16x16x32_bf16 v[62:65], v[86:89], v[188:191], v[62:65]
	v_mfma_f32_16x16x32_bf16 v[58:61], v[102:105], v[188:191], v[58:61]
	v_mfma_f32_16x16x32_bf16 v[46:49], v[86:89], v[196:199], v[46:49]
	v_mfma_f32_16x16x32_bf16 v[42:45], v[102:105], v[196:199], v[42:45]
	v_mfma_f32_16x16x32_bf16 v[30:33], v[86:89], v[210:213], v[30:33]
	v_mfma_f32_16x16x32_bf16 v[26:29], v[102:105], v[210:213], v[26:29]
	v_mfma_f32_16x16x32_bf16 v[14:17], v[86:89], v[218:221], v[14:17]
	v_mfma_f32_16x16x32_bf16 v[10:13], v[102:105], v[218:221], v[10:13]
	v_mfma_f32_16x16x32_bf16 v[54:57], v[154:157], v[184:187], v[54:57]
	v_mfma_f32_16x16x32_bf16 v[50:53], v[176:179], v[184:187], v[50:53]
	v_mfma_f32_16x16x32_bf16 v[38:41], v[154:157], v[192:195], v[38:41]
	v_mfma_f32_16x16x32_bf16 v[34:37], v[176:179], v[192:195], v[34:37]
	v_mfma_f32_16x16x32_bf16 v[22:25], v[154:157], v[200:203], v[22:25]
	v_mfma_f32_16x16x32_bf16 v[18:21], v[176:179], v[200:203], v[18:21]
	v_mfma_f32_16x16x32_bf16 v[6:9], v[154:157], v[214:217], v[6:9]
	v_mfma_f32_16x16x32_bf16 v[2:5], v[176:179], v[214:217], v[2:5]
	v_mfma_f32_16x16x32_bf16 v[54:57], v[168:171], v[188:191], v[54:57]
	v_mfma_f32_16x16x32_bf16 v[50:53], v[180:183], v[188:191], v[50:53]
	v_mfma_f32_16x16x32_bf16 v[38:41], v[168:171], v[196:199], v[38:41]
	v_mfma_f32_16x16x32_bf16 v[34:37], v[180:183], v[196:199], v[34:37]
	v_mfma_f32_16x16x32_bf16 v[22:25], v[168:171], v[210:213], v[22:25]
	v_mfma_f32_16x16x32_bf16 v[18:21], v[180:183], v[210:213], v[18:21]
	v_mfma_f32_16x16x32_bf16 v[6:9], v[168:171], v[218:221], v[6:9]
	v_mfma_f32_16x16x32_bf16 v[2:5], v[180:183], v[218:221], v[2:5]
	s_barrier
	s_add_i32 s58, 0, 0x18000
	s_add_i32 s59, 0, 0x1c000
	v_add_u32_e32 v102, s58, v172
	v_add_u32_e32 v175, s59, v172
	ds_read_b128 v[82:85], v102
	ds_read_b128 v[86:89], v102 offset:1024
	ds_read_b128 v[98:101], v102 offset:2048
	ds_read_b128 v[102:105], v102 offset:3072
	ds_read_b128 v[154:157], v175
	ds_read_b128 v[168:171], v175 offset:1024
	ds_read_b128 v[176:179], v175 offset:2048
	ds_read_b128 v[180:183], v175 offset:3072
	s_add_u32 s48, s48, 0x80000
	s_addc_u32 s49, s49, 0
	s_mov_b32 m0, s16
	ds_read_b128 v[184:187], v174 offset:32768
	ds_read_b128 v[188:191], v174 offset:33792
	ds_read_b128 v[192:195], v174 offset:34816
	ds_read_b128 v[196:199], v174 offset:35840
	ds_read_b128 v[200:203], v174 offset:36864
	ds_read_b128 v[210:213], v174 offset:37888
	ds_read_b128 v[214:217], v174 offset:38912
	ds_read_b128 v[218:221], v174 offset:39936
	global_load_lds_dwordx4 v162, s[48:49]
	s_mov_b32 m0, s18
	s_nop 0
	global_load_lds_dwordx4 v160, s[48:49]
	s_waitcnt vmcnt(8) lgkmcnt(0)
	s_barrier
	v_mfma_f32_16x16x32_bf16 v[142:145], v[82:85], v[184:187], v[142:145]
	v_mfma_f32_16x16x32_bf16 v[138:141], v[98:101], v[184:187], v[138:141]
	v_mfma_f32_16x16x32_bf16 v[126:129], v[82:85], v[192:195], v[126:129]
	v_mfma_f32_16x16x32_bf16 v[122:125], v[98:101], v[192:195], v[122:125]
	v_mfma_f32_16x16x32_bf16 v[110:113], v[82:85], v[200:203], v[110:113]
	v_mfma_f32_16x16x32_bf16 v[106:109], v[98:101], v[200:203], v[106:109]
	v_mfma_f32_16x16x32_bf16 v[78:81], v[82:85], v[214:217], v[78:81]
	v_mfma_f32_16x16x32_bf16 v[74:77], v[98:101], v[214:217], v[74:77]
	v_mfma_f32_16x16x32_bf16 v[142:145], v[86:89], v[188:191], v[142:145]
	v_mfma_f32_16x16x32_bf16 v[138:141], v[102:105], v[188:191], v[138:141]
	v_mfma_f32_16x16x32_bf16 v[126:129], v[86:89], v[196:199], v[126:129]
	v_mfma_f32_16x16x32_bf16 v[122:125], v[102:105], v[196:199], v[122:125]
	v_mfma_f32_16x16x32_bf16 v[110:113], v[86:89], v[210:213], v[110:113]
	v_mfma_f32_16x16x32_bf16 v[106:109], v[102:105], v[210:213], v[106:109]
	v_mfma_f32_16x16x32_bf16 v[78:81], v[86:89], v[218:221], v[78:81]
	v_mfma_f32_16x16x32_bf16 v[74:77], v[102:105], v[218:221], v[74:77]
	v_mfma_f32_16x16x32_bf16 v[134:137], v[154:157], v[184:187], v[134:137]
	v_mfma_f32_16x16x32_bf16 v[130:133], v[176:179], v[184:187], v[130:133]
	v_mfma_f32_16x16x32_bf16 v[118:121], v[154:157], v[192:195], v[118:121]
	v_mfma_f32_16x16x32_bf16 v[114:117], v[176:179], v[192:195], v[114:117]
	v_mfma_f32_16x16x32_bf16 v[94:97], v[154:157], v[200:203], v[94:97]
	v_mfma_f32_16x16x32_bf16 v[90:93], v[176:179], v[200:203], v[90:93]
	v_mfma_f32_16x16x32_bf16 v[70:73], v[154:157], v[214:217], v[70:73]
	v_mfma_f32_16x16x32_bf16 v[66:69], v[176:179], v[214:217], v[66:69]
	v_mfma_f32_16x16x32_bf16 v[134:137], v[168:171], v[188:191], v[134:137]
	v_mfma_f32_16x16x32_bf16 v[130:133], v[180:183], v[188:191], v[130:133]
	v_mfma_f32_16x16x32_bf16 v[118:121], v[168:171], v[196:199], v[118:121]
	v_mfma_f32_16x16x32_bf16 v[114:117], v[180:183], v[196:199], v[114:117]
	v_mfma_f32_16x16x32_bf16 v[94:97], v[168:171], v[210:213], v[94:97]
	v_mfma_f32_16x16x32_bf16 v[90:93], v[180:183], v[210:213], v[90:93]
	v_mfma_f32_16x16x32_bf16 v[70:73], v[168:171], v[218:221], v[70:73]
	v_mfma_f32_16x16x32_bf16 v[66:69], v[180:183], v[218:221], v[66:69]
	s_barrier
	s_add_i32 s48, s58, s5
	v_lshl_add_u64 v[222:223], v[222:223], 0, s[34:35]
	s_mov_b32 m0, s48
	ds_read_b128 v[184:187], v174 offset:49152
	ds_read_b128 v[188:191], v174 offset:50176
	ds_read_b128 v[192:195], v174 offset:51200
	ds_read_b128 v[196:199], v174 offset:52224
	ds_read_b128 v[200:203], v174 offset:53248
	ds_read_b128 v[210:213], v174 offset:54272
	ds_read_b128 v[214:217], v174 offset:55296
	ds_read_b128 v[218:221], v174 offset:56320
	global_load_lds_dwordx4 v[222:223], off
	s_add_i32 m0, s48, 0x2000
	s_add_u32 s46, s46, 0x80080
	v_lshl_add_u64 v[222:223], v[224:225], 0, s[34:35]
	s_addc_u32 s47, s47, 0
	s_add_i32 s48, s59, s5
	global_load_lds_dwordx4 v[222:223], off
	s_mov_b32 m0, s48
	s_nop 0
	global_load_lds_dwordx4 v0, s[46:47]
	s_add_i32 m0, s48, 0x2000
	s_nop 0
	global_load_lds_dwordx4 v158, s[46:47]
	v_lshl_add_u64 v[222:223], v[226:227], 0, s[34:35]
	s_mov_b32 m0, s25
	s_nop 0
	global_load_lds_dwordx4 v[222:223], off
	v_lshl_add_u64 v[222:223], v[228:229], 0, s[34:35]
	s_mov_b32 m0, s33
	s_nop 0
	global_load_lds_dwordx4 v[222:223], off
	s_waitcnt vmcnt(8) lgkmcnt(0)
	s_barrier
	v_mfma_f32_16x16x32_bf16 v[62:65], v[82:85], v[184:187], v[62:65]
	v_mfma_f32_16x16x32_bf16 v[58:61], v[98:101], v[184:187], v[58:61]
	v_mfma_f32_16x16x32_bf16 v[46:49], v[82:85], v[192:195], v[46:49]
	v_mfma_f32_16x16x32_bf16 v[42:45], v[98:101], v[192:195], v[42:45]
	v_mfma_f32_16x16x32_bf16 v[30:33], v[82:85], v[200:203], v[30:33]
	v_mfma_f32_16x16x32_bf16 v[26:29], v[98:101], v[200:203], v[26:29]
	v_mfma_f32_16x16x32_bf16 v[14:17], v[82:85], v[214:217], v[14:17]
	v_mfma_f32_16x16x32_bf16 v[10:13], v[98:101], v[214:217], v[10:13]
	v_mfma_f32_16x16x32_bf16 v[62:65], v[86:89], v[188:191], v[62:65]
	v_mfma_f32_16x16x32_bf16 v[58:61], v[102:105], v[188:191], v[58:61]
	v_mfma_f32_16x16x32_bf16 v[46:49], v[86:89], v[196:199], v[46:49]
	v_mfma_f32_16x16x32_bf16 v[42:45], v[102:105], v[196:199], v[42:45]
	v_mfma_f32_16x16x32_bf16 v[30:33], v[86:89], v[210:213], v[30:33]
	v_mfma_f32_16x16x32_bf16 v[26:29], v[102:105], v[210:213], v[26:29]
	v_mfma_f32_16x16x32_bf16 v[14:17], v[86:89], v[218:221], v[14:17]
	v_mfma_f32_16x16x32_bf16 v[10:13], v[102:105], v[218:221], v[10:13]
	v_mfma_f32_16x16x32_bf16 v[54:57], v[154:157], v[184:187], v[54:57]
	v_mfma_f32_16x16x32_bf16 v[50:53], v[176:179], v[184:187], v[50:53]
	v_mfma_f32_16x16x32_bf16 v[38:41], v[154:157], v[192:195], v[38:41]
	v_mfma_f32_16x16x32_bf16 v[34:37], v[176:179], v[192:195], v[34:37]
	v_mfma_f32_16x16x32_bf16 v[22:25], v[154:157], v[200:203], v[22:25]
	v_mfma_f32_16x16x32_bf16 v[18:21], v[176:179], v[200:203], v[18:21]
	v_mfma_f32_16x16x32_bf16 v[6:9], v[154:157], v[214:217], v[6:9]
	v_mfma_f32_16x16x32_bf16 v[2:5], v[176:179], v[214:217], v[2:5]
	v_mfma_f32_16x16x32_bf16 v[54:57], v[168:171], v[188:191], v[54:57]
	v_mfma_f32_16x16x32_bf16 v[50:53], v[180:183], v[188:191], v[50:53]
	v_mfma_f32_16x16x32_bf16 v[38:41], v[168:171], v[196:199], v[38:41]
	v_mfma_f32_16x16x32_bf16 v[34:37], v[180:183], v[196:199], v[34:37]
	v_mfma_f32_16x16x32_bf16 v[22:25], v[168:171], v[210:213], v[22:25]
	v_mfma_f32_16x16x32_bf16 v[18:21], v[180:183], v[210:213], v[18:21]
	v_mfma_f32_16x16x32_bf16 v[6:9], v[168:171], v[218:221], v[6:9]
	v_mfma_f32_16x16x32_bf16 v[2:5], v[180:183], v[218:221], v[2:5]
	s_barrier
	s_add_i32 s57, s57, 2
	s_add_u32 s44, s44, 0x100
	s_addc_u32 s45, s45, 0
	s_add_u32 s55, s55, 0x100
	s_addc_u32 s56, s56, 0
	s_cmp_gt_u32 s57, 29
	s_cbranch_scc0 .LBB0_516
	s_setprio 0
	s_and_b64 vcc, exec, s[10:11]
	s_cbranch_vccz .LBB0_519
	s_barrier

.Lgprio2:
.LBB0_604:
	s_add_u32 s22, s6, 0xfff80080
	s_addc_u32 s23, s7, -1
	s_add_i32 s54, 0, 0x10000
	s_cmp_eq_u32 s53, 28
	s_cselect_b32 s47, s18, s23
	s_cselect_b32 s46, s19, s22
	s_cselect_b32 s23, s21, s52
	s_cselect_b32 s22, s25, s41
	s_add_i32 s56, 0, 0x14000
	v_add_u32_e32 v162, s54, v175
	v_add_u32_e32 v174, s56, v175
	ds_read_b128 v[130:133], v162
	ds_read_b128 v[134:137], v162 offset:1024
	ds_read_b128 v[154:157], v162 offset:2048
	ds_read_b128 v[162:165], v162 offset:3072
	ds_read_b128 v[166:169], v174
	ds_read_b128 v[170:173], v174 offset:1024
	ds_read_b128 v[180:183], v174 offset:2048
	ds_read_b128 v[184:187], v174 offset:3072
	s_add_i32 m0, s16, 0xc000
	ds_read_b128 v[188:191], v179
	ds_read_b128 v[192:195], v179 offset:1024
	ds_read_b128 v[196:199], v179 offset:2048
	ds_read_b128 v[200:203], v179 offset:3072
	ds_read_b128 v[210:213], v179 offset:4096
	ds_read_b128 v[214:217], v179 offset:5120
	ds_read_b128 v[218:221], v179 offset:6144
	ds_read_b128 v[222:225], v179 offset:7168
	global_load_lds_dwordx4 v158, s[6:7]
	s_add_i32 m0, s16, 0xe000
	s_nop 0
	global_load_lds_dwordx4 v160, s[6:7]
	s_waitcnt vmcnt(8) lgkmcnt(0)
	s_barrier
	v_mfma_f32_16x16x32_bf16 v[126:129], v[130:133], v[188:191], v[126:129]
	v_mfma_f32_16x16x32_bf16 v[122:125], v[154:157], v[188:191], v[122:125]
	v_mfma_f32_16x16x32_bf16 v[110:113], v[130:133], v[196:199], v[110:113]
	v_mfma_f32_16x16x32_bf16 v[106:109], v[154:157], v[196:199], v[106:109]
	v_mfma_f32_16x16x32_bf16 v[94:97], v[130:133], v[210:213], v[94:97]
	v_mfma_f32_16x16x32_bf16 v[90:93], v[154:157], v[210:213], v[90:93]
	v_mfma_f32_16x16x32_bf16 v[78:81], v[130:133], v[218:221], v[78:81]
	v_mfma_f32_16x16x32_bf16 v[74:77], v[154:157], v[218:221], v[74:77]
	v_mfma_f32_16x16x32_bf16 v[126:129], v[134:137], v[192:195], v[126:129]
	v_mfma_f32_16x16x32_bf16 v[122:125], v[162:165], v[192:195], v[122:125]
	v_mfma_f32_16x16x32_bf16 v[110:113], v[134:137], v[200:203], v[110:113]
	v_mfma_f32_16x16x32_bf16 v[106:109], v[162:165], v[200:203], v[106:109]
	v_mfma_f32_16x16x32_bf16 v[94:97], v[134:137], v[214:217], v[94:97]
	v_mfma_f32_16x16x32_bf16 v[90:93], v[162:165], v[214:217], v[90:93]
	v_mfma_f32_16x16x32_bf16 v[78:81], v[134:137], v[222:225], v[78:81]
	v_mfma_f32_16x16x32_bf16 v[74:77], v[162:165], v[222:225], v[74:77]
	v_mfma_f32_16x16x32_bf16 v[118:121], v[166:169], v[188:191], v[118:121]
	v_mfma_f32_16x16x32_bf16 v[114:117], v[180:183], v[188:191], v[114:117]
	v_mfma_f32_16x16x32_bf16 v[102:105], v[166:169], v[196:199], v[102:105]
	v_mfma_f32_16x16x32_bf16 v[98:101], v[180:183], v[196:199], v[98:101]
	v_mfma_f32_16x16x32_bf16 v[86:89], v[166:169], v[210:213], v[86:89]
	v_mfma_f32_16x16x32_bf16 v[82:85], v[180:183], v[210:213], v[82:85]
	v_mfma_f32_16x16x32_bf16 v[70:73], v[166:169], v[218:221], v[70:73]
	v_mfma_f32_16x16x32_bf16 v[66:69], v[180:183], v[218:221], v[66:69]
	v_mfma_f32_16x16x32_bf16 v[118:121], v[170:173], v[192:195], v[118:121]
	v_mfma_f32_16x16x32_bf16 v[114:117], v[184:187], v[192:195], v[114:117]
	v_mfma_f32_16x16x32_bf16 v[102:105], v[170:173], v[200:203], v[102:105]
	v_mfma_f32_16x16x32_bf16 v[98:101], v[184:187], v[200:203], v[98:101]
	v_mfma_f32_16x16x32_bf16 v[86:89], v[170:173], v[214:217], v[86:89]
	v_mfma_f32_16x16x32_bf16 v[82:85], v[184:187], v[214:217], v[82:85]
	v_mfma_f32_16x16x32_bf16 v[70:73], v[170:173], v[222:225], v[70:73]
	v_mfma_f32_16x16x32_bf16 v[66:69], v[184:187], v[222:225], v[66:69]
	s_barrier
	s_add_i32 s54, s54, s15
	v_lshl_add_u64 v[226:227], s[22:23], 0, v[142:143]
	s_mov_b32 m0, s54
	ds_read_b128 v[188:191], v179 offset:16384
	ds_read_b128 v[192:195], v179 offset:17408
	ds_read_b128 v[196:199], v179 offset:18432
	ds_read_b128 v[200:203], v179 offset:19456
	ds_read_b128 v[210:213], v179 offset:20480
	ds_read_b128 v[214:217], v179 offset:21504
	ds_read_b128 v[218:221], v179 offset:22528
	ds_read_b128 v[222:225], v179 offset:23552
	global_load_lds_dwordx4 v[226:227], off
	s_add_i32 m0, s54, 0x2000
	s_add_u32 s54, s22, 0x80000
	v_lshl_add_u64 v[228:229], s[22:23], 0, v[138:139]
	s_addc_u32 s55, s23, 0
	s_add_i32 s56, s56, s15
	global_load_lds_dwordx4 v[228:229], off
	s_mov_b32 m0, s56
	v_lshl_add_u64 v[232:233], s[46:47], 0, v[140:141]
	global_load_lds_dwordx4 v142, s[54:55]
	s_add_i32 m0, s56, 0x2000
	s_nop 0
	global_load_lds_dwordx4 v138, s[54:55]
	v_lshl_add_u64 v[230:231], s[46:47], 0, v[144:145]
	s_mov_b32 m0, s16
	s_nop 0
	global_load_lds_dwordx4 v[230:231], off
	s_mov_b32 m0, s33
	s_nop 0
	global_load_lds_dwordx4 v[232:233], off
	s_waitcnt vmcnt(8) lgkmcnt(0)
	s_barrier
	v_mfma_f32_16x16x32_bf16 v[62:65], v[130:133], v[188:191], v[62:65]
	v_mfma_f32_16x16x32_bf16 v[58:61], v[154:157], v[188:191], v[58:61]
	v_mfma_f32_16x16x32_bf16 v[46:49], v[130:133], v[196:199], v[46:49]
	v_mfma_f32_16x16x32_bf16 v[42:45], v[154:157], v[196:199], v[42:45]
	v_mfma_f32_16x16x32_bf16 v[30:33], v[130:133], v[210:213], v[30:33]
	v_mfma_f32_16x16x32_bf16 v[26:29], v[154:157], v[210:213], v[26:29]
	v_mfma_f32_16x16x32_bf16 v[14:17], v[130:133], v[218:221], v[14:17]
	v_mfma_f32_16x16x32_bf16 v[10:13], v[154:157], v[218:221], v[10:13]
	v_mfma_f32_16x16x32_bf16 v[62:65], v[134:137], v[192:195], v[62:65]
	v_mfma_f32_16x16x32_bf16 v[58:61], v[162:165], v[192:195], v[58:61]
	v_mfma_f32_16x16x32_bf16 v[46:49], v[134:137], v[200:203], v[46:49]
	v_mfma_f32_16x16x32_bf16 v[42:45], v[162:165], v[200:203], v[42:45]
	v_mfma_f32_16x16x32_bf16 v[30:33], v[134:137], v[214:217], v[30:33]
	v_mfma_f32_16x16x32_bf16 v[26:29], v[162:165], v[214:217], v[26:29]
	v_mfma_f32_16x16x32_bf16 v[14:17], v[134:137], v[222:225], v[14:17]
	v_mfma_f32_16x16x32_bf16 v[10:13], v[162:165], v[222:225], v[10:13]
	v_mfma_f32_16x16x32_bf16 v[54:57], v[166:169], v[188:191], v[54:57]
	v_mfma_f32_16x16x32_bf16 v[50:53], v[180:183], v[188:191], v[50:53]
	v_mfma_f32_16x16x32_bf16 v[38:41], v[166:169], v[196:199], v[38:41]
	v_mfma_f32_16x16x32_bf16 v[34:37], v[180:183], v[196:199], v[34:37]
	v_mfma_f32_16x16x32_bf16 v[22:25], v[166:169], v[210:213], v[22:25]
	v_mfma_f32_16x16x32_bf16 v[18:21], v[180:183], v[210:213], v[18:21]
	v_mfma_f32_16x16x32_bf16 v[6:9], v[166:169], v[218:221], v[6:9]
	v_mfma_f32_16x16x32_bf16 v[2:5], v[180:183], v[218:221], v[2:5]
	v_mfma_f32_16x16x32_bf16 v[54:57], v[170:173], v[192:195], v[54:57]
	v_mfma_f32_16x16x32_bf16 v[50:53], v[184:187], v[192:195], v[50:53]
	v_mfma_f32_16x16x32_bf16 v[38:41], v[170:173], v[200:203], v[38:41]
	v_mfma_f32_16x16x32_bf16 v[34:37], v[184:187], v[200:203], v[34:37]
	v_mfma_f32_16x16x32_bf16 v[22:25], v[170:173], v[214:217], v[22:25]
	v_mfma_f32_16x16x32_bf16 v[18:21], v[184:187], v[214:217], v[18:21]
	v_mfma_f32_16x16x32_bf16 v[6:9], v[170:173], v[222:225], v[6:9]
	v_mfma_f32_16x16x32_bf16 v[2:5], v[184:187], v[222:225], v[2:5]
	s_barrier
	s_add_i32 s54, 0, 0x18000
	s_add_i32 s55, 0, 0x1c000
	v_add_u32_e32 v162, s54, v175
	v_add_u32_e32 v174, s55, v175
	ds_read_b128 v[130:133], v162
	ds_read_b128 v[134:137], v162 offset:1024
	ds_read_b128 v[154:157], v162 offset:2048
	ds_read_b128 v[162:165], v162 offset:3072
	ds_read_b128 v[166:169], v174
	ds_read_b128 v[170:173], v174 offset:1024
	ds_read_b128 v[180:183], v174 offset:2048
	ds_read_b128 v[184:187], v174 offset:3072
	s_add_u32 s46, s46, 0x80000
	s_addc_u32 s47, s47, 0
	s_mov_b32 m0, s37
	ds_read_b128 v[188:191], v179 offset:32768
	ds_read_b128 v[192:195], v179 offset:33792
	ds_read_b128 v[196:199], v179 offset:34816
	ds_read_b128 v[200:203], v179 offset:35840
	ds_read_b128 v[210:213], v179 offset:36864
	ds_read_b128 v[214:217], v179 offset:37888
	ds_read_b128 v[218:221], v179 offset:38912
	ds_read_b128 v[222:225], v179 offset:39936
	global_load_lds_dwordx4 v144, s[46:47]
	s_mov_b32 m0, s48
	s_nop 0
	global_load_lds_dwordx4 v140, s[46:47]
	s_waitcnt vmcnt(8) lgkmcnt(0)
	s_barrier
	v_mfma_f32_16x16x32_bf16 v[126:129], v[130:133], v[188:191], v[126:129]
	v_mfma_f32_16x16x32_bf16 v[122:125], v[154:157], v[188:191], v[122:125]
	v_mfma_f32_16x16x32_bf16 v[110:113], v[130:133], v[196:199], v[110:113]
	v_mfma_f32_16x16x32_bf16 v[106:109], v[154:157], v[196:199], v[106:109]
	v_mfma_f32_16x16x32_bf16 v[94:97], v[130:133], v[210:213], v[94:97]
	v_mfma_f32_16x16x32_bf16 v[90:93], v[154:157], v[210:213], v[90:93]
	v_mfma_f32_16x16x32_bf16 v[78:81], v[130:133], v[218:221], v[78:81]
	v_mfma_f32_16x16x32_bf16 v[74:77], v[154:157], v[218:221], v[74:77]
	v_mfma_f32_16x16x32_bf16 v[126:129], v[134:137], v[192:195], v[126:129]
	v_mfma_f32_16x16x32_bf16 v[122:125], v[162:165], v[192:195], v[122:125]
	v_mfma_f32_16x16x32_bf16 v[110:113], v[134:137], v[200:203], v[110:113]
	v_mfma_f32_16x16x32_bf16 v[106:109], v[162:165], v[200:203], v[106:109]
	v_mfma_f32_16x16x32_bf16 v[94:97], v[134:137], v[214:217], v[94:97]
	v_mfma_f32_16x16x32_bf16 v[90:93], v[162:165], v[214:217], v[90:93]
	v_mfma_f32_16x16x32_bf16 v[78:81], v[134:137], v[222:225], v[78:81]
	v_mfma_f32_16x16x32_bf16 v[74:77], v[162:165], v[222:225], v[74:77]
	v_mfma_f32_16x16x32_bf16 v[118:121], v[166:169], v[188:191], v[118:121]
	v_mfma_f32_16x16x32_bf16 v[114:117], v[180:183], v[188:191], v[114:117]
	v_mfma_f32_16x16x32_bf16 v[102:105], v[166:169], v[196:199], v[102:105]
	v_mfma_f32_16x16x32_bf16 v[98:101], v[180:183], v[196:199], v[98:101]
	v_mfma_f32_16x16x32_bf16 v[86:89], v[166:169], v[210:213], v[86:89]
	v_mfma_f32_16x16x32_bf16 v[82:85], v[180:183], v[210:213], v[82:85]
	v_mfma_f32_16x16x32_bf16 v[70:73], v[166:169], v[218:221], v[70:73]
	v_mfma_f32_16x16x32_bf16 v[66:69], v[180:183], v[218:221], v[66:69]
	v_mfma_f32_16x16x32_bf16 v[118:121], v[170:173], v[192:195], v[118:121]
	v_mfma_f32_16x16x32_bf16 v[114:117], v[184:187], v[192:195], v[114:117]
	v_mfma_f32_16x16x32_bf16 v[102:105], v[170:173], v[200:203], v[102:105]
	v_mfma_f32_16x16x32_bf16 v[98:101], v[184:187], v[200:203], v[98:101]
	v_mfma_f32_16x16x32_bf16 v[86:89], v[170:173], v[214:217], v[86:89]
	v_mfma_f32_16x16x32_bf16 v[82:85], v[184:187], v[214:217], v[82:85]
	v_mfma_f32_16x16x32_bf16 v[70:73], v[170:173], v[222:225], v[70:73]
	v_mfma_f32_16x16x32_bf16 v[66:69], v[184:187], v[222:225], v[66:69]
	s_barrier
	s_add_i32 s46, s54, s15
	v_lshl_add_u64 v[226:227], v[226:227], 0, s[34:35]
	s_mov_b32 m0, s46
	ds_read_b128 v[188:191], v179 offset:49152
	ds_read_b128 v[192:195], v179 offset:50176
	ds_read_b128 v[196:199], v179 offset:51200
	ds_read_b128 v[200:203], v179 offset:52224
	ds_read_b128 v[210:213], v179 offset:53248
	ds_read_b128 v[214:217], v179 offset:54272
	ds_read_b128 v[218:221], v179 offset:55296
	ds_read_b128 v[222:225], v179 offset:56320
	global_load_lds_dwordx4 v[226:227], off
	s_add_i32 m0, s46, 0x2000
	s_add_u32 s22, s22, 0x80080
	v_lshl_add_u64 v[226:227], v[228:229], 0, s[34:35]
	s_addc_u32 s23, s23, 0
	s_add_i32 s46, s55, s15
	global_load_lds_dwordx4 v[226:227], off
	s_mov_b32 m0, s46
	s_nop 0
	global_load_lds_dwordx4 v142, s[22:23]
	s_add_i32 m0, s46, 0x2000
	s_nop 0
	global_load_lds_dwordx4 v138, s[22:23]
	v_lshl_add_u64 v[226:227], v[230:231], 0, s[34:35]
	s_mov_b32 m0, s49
	s_nop 0
	global_load_lds_dwordx4 v[226:227], off
	v_lshl_add_u64 v[226:227], v[232:233], 0, s[34:35]
	s_mov_b32 m0, s50
	s_nop 0
	global_load_lds_dwordx4 v[226:227], off
	s_waitcnt vmcnt(8) lgkmcnt(0)
	s_barrier
	v_mfma_f32_16x16x32_bf16 v[62:65], v[130:133], v[188:191], v[62:65]
	v_mfma_f32_16x16x32_bf16 v[58:61], v[154:157], v[188:191], v[58:61]
	v_mfma_f32_16x16x32_bf16 v[46:49], v[130:133], v[196:199], v[46:49]
	v_mfma_f32_16x16x32_bf16 v[42:45], v[154:157], v[196:199], v[42:45]
	v_mfma_f32_16x16x32_bf16 v[30:33], v[130:133], v[210:213], v[30:33]
	v_mfma_f32_16x16x32_bf16 v[26:29], v[154:157], v[210:213], v[26:29]
	v_mfma_f32_16x16x32_bf16 v[14:17], v[130:133], v[218:221], v[14:17]
	v_mfma_f32_16x16x32_bf16 v[10:13], v[154:157], v[218:221], v[10:13]
	v_mfma_f32_16x16x32_bf16 v[62:65], v[134:137], v[192:195], v[62:65]
	v_mfma_f32_16x16x32_bf16 v[58:61], v[162:165], v[192:195], v[58:61]
	v_mfma_f32_16x16x32_bf16 v[46:49], v[134:137], v[200:203], v[46:49]
	v_mfma_f32_16x16x32_bf16 v[42:45], v[162:165], v[200:203], v[42:45]
	v_mfma_f32_16x16x32_bf16 v[30:33], v[134:137], v[214:217], v[30:33]
	v_mfma_f32_16x16x32_bf16 v[26:29], v[162:165], v[214:217], v[26:29]
	v_mfma_f32_16x16x32_bf16 v[14:17], v[134:137], v[222:225], v[14:17]
	v_mfma_f32_16x16x32_bf16 v[10:13], v[162:165], v[222:225], v[10:13]
	v_mfma_f32_16x16x32_bf16 v[54:57], v[166:169], v[188:191], v[54:57]
	v_mfma_f32_16x16x32_bf16 v[50:53], v[180:183], v[188:191], v[50:53]
	v_mfma_f32_16x16x32_bf16 v[38:41], v[166:169], v[196:199], v[38:41]
	v_mfma_f32_16x16x32_bf16 v[34:37], v[180:183], v[196:199], v[34:37]
	v_mfma_f32_16x16x32_bf16 v[22:25], v[166:169], v[210:213], v[22:25]
	v_mfma_f32_16x16x32_bf16 v[18:21], v[180:183], v[210:213], v[18:21]
	v_mfma_f32_16x16x32_bf16 v[6:9], v[166:169], v[218:221], v[6:9]
	v_mfma_f32_16x16x32_bf16 v[2:5], v[180:183], v[218:221], v[2:5]
	v_mfma_f32_16x16x32_bf16 v[54:57], v[170:173], v[192:195], v[54:57]
	v_mfma_f32_16x16x32_bf16 v[50:53], v[184:187], v[192:195], v[50:53]
	v_mfma_f32_16x16x32_bf16 v[38:41], v[170:173], v[200:203], v[38:41]
	v_mfma_f32_16x16x32_bf16 v[34:37], v[184:187], v[200:203], v[34:37]
	v_mfma_f32_16x16x32_bf16 v[22:25], v[170:173], v[214:217], v[22:25]
	v_mfma_f32_16x16x32_bf16 v[18:21], v[184:187], v[214:217], v[18:21]
	v_mfma_f32_16x16x32_bf16 v[6:9], v[170:173], v[222:225], v[6:9]
	v_mfma_f32_16x16x32_bf16 v[2:5], v[184:187], v[222:225], v[2:5]
	s_barrier
	s_add_i32 s53, s53, 2
	s_add_u32 s6, s6, 0x100
	s_addc_u32 s7, s7, 0
	s_add_u32 s41, s41, 0x100
	s_addc_u32 s52, s52, 0
	s_cmp_gt_u32 s53, 29
	s_cbranch_scc0 .LBB0_604
	s_setprio 0
	s_and_b64 vcc, exec, s[12:13]
	s_cbranch_vccz .LBB0_607
	s_barrier

.Lgprio3:
.LBB0_728:
	s_add_u32 s42, s22, 0x100
	s_addc_u32 s43, s23, 0
	s_add_i32 s50, 0, 0x10000
	s_cmpk_eq_i32 s25, 0x54
	s_cselect_b32 s49, s21, s43
	s_cselect_b32 s48, s20, s42
	s_cselect_b32 s47, s45, s19
	s_cselect_b32 s46, s44, s18
	s_add_i32 s51, 0, 0x14000
	v_add_u32_e32 v54, s50, v176
	v_add_u32_e32 v179, s51, v176
	ds_read_b128 v[42:45], v54
	ds_read_b128 v[46:49], v54 offset:1024
	ds_read_b128 v[50:53], v54 offset:2048
	ds_read_b128 v[54:57], v54 offset:3072
	ds_read_b128 v[154:157], v179
	ds_read_b128 v[168:171], v179 offset:1024
	ds_read_b128 v[172:175], v179 offset:2048
	ds_read_b128 v[180:183], v179 offset:3072
	s_add_i32 m0, s33, 0xc000
	ds_read_b128 v[184:187], v178
	ds_read_b128 v[188:191], v178 offset:1024
	ds_read_b128 v[192:195], v178 offset:2048
	ds_read_b128 v[196:199], v178 offset:3072
	ds_read_b128 v[200:203], v178 offset:4096
	ds_read_b128 v[210:213], v178 offset:5120
	ds_read_b128 v[214:217], v178 offset:6144
	ds_read_b128 v[218:221], v178 offset:7168
	global_load_lds_dwordx4 v164, s[22:23]
	s_add_i32 m0, s33, 0xe000
	s_nop 0
	global_load_lds_dwordx4 v166, s[22:23]
	s_waitcnt vmcnt(8) lgkmcnt(0)
	s_barrier
	v_mfma_f32_16x16x32_bf16 v[142:145], v[42:45], v[184:187], v[142:145]
	v_mfma_f32_16x16x32_bf16 v[138:141], v[50:53], v[184:187], v[138:141]
	v_mfma_f32_16x16x32_bf16 v[126:129], v[42:45], v[192:195], v[126:129]
	v_mfma_f32_16x16x32_bf16 v[122:125], v[50:53], v[192:195], v[122:125]
	v_mfma_f32_16x16x32_bf16 v[110:113], v[42:45], v[200:203], v[110:113]
	v_mfma_f32_16x16x32_bf16 v[106:109], v[50:53], v[200:203], v[106:109]
	v_mfma_f32_16x16x32_bf16 v[94:97], v[42:45], v[214:217], v[94:97]
	v_mfma_f32_16x16x32_bf16 v[90:93], v[50:53], v[214:217], v[90:93]
	v_mfma_f32_16x16x32_bf16 v[142:145], v[46:49], v[188:191], v[142:145]
	v_mfma_f32_16x16x32_bf16 v[138:141], v[54:57], v[188:191], v[138:141]
	v_mfma_f32_16x16x32_bf16 v[126:129], v[46:49], v[196:199], v[126:129]
	v_mfma_f32_16x16x32_bf16 v[122:125], v[54:57], v[196:199], v[122:125]
	v_mfma_f32_16x16x32_bf16 v[110:113], v[46:49], v[210:213], v[110:113]
	v_mfma_f32_16x16x32_bf16 v[106:109], v[54:57], v[210:213], v[106:109]
	v_mfma_f32_16x16x32_bf16 v[94:97], v[46:49], v[218:221], v[94:97]
	v_mfma_f32_16x16x32_bf16 v[90:93], v[54:57], v[218:221], v[90:93]
	v_mfma_f32_16x16x32_bf16 v[134:137], v[154:157], v[184:187], v[134:137]
	v_mfma_f32_16x16x32_bf16 v[130:133], v[172:175], v[184:187], v[130:133]
	v_mfma_f32_16x16x32_bf16 v[118:121], v[154:157], v[192:195], v[118:121]
	v_mfma_f32_16x16x32_bf16 v[114:117], v[172:175], v[192:195], v[114:117]
	v_mfma_f32_16x16x32_bf16 v[102:105], v[154:157], v[200:203], v[102:105]
	v_mfma_f32_16x16x32_bf16 v[98:101], v[172:175], v[200:203], v[98:101]
	v_mfma_f32_16x16x32_bf16 v[86:89], v[154:157], v[214:217], v[86:89]
	v_mfma_f32_16x16x32_bf16 v[82:85], v[172:175], v[214:217], v[82:85]
	v_mfma_f32_16x16x32_bf16 v[134:137], v[168:171], v[188:191], v[134:137]
	v_mfma_f32_16x16x32_bf16 v[130:133], v[180:183], v[188:191], v[130:133]
	v_mfma_f32_16x16x32_bf16 v[118:121], v[168:171], v[196:199], v[118:121]
	v_mfma_f32_16x16x32_bf16 v[114:117], v[180:183], v[196:199], v[114:117]
	v_mfma_f32_16x16x32_bf16 v[102:105], v[168:171], v[210:213], v[102:105]
	v_mfma_f32_16x16x32_bf16 v[98:101], v[180:183], v[210:213], v[98:101]
	v_mfma_f32_16x16x32_bf16 v[86:89], v[168:171], v[218:221], v[86:89]
	v_mfma_f32_16x16x32_bf16 v[82:85], v[180:183], v[218:221], v[82:85]
	s_barrier
	s_add_i32 s22, s50, s16
	v_lshl_add_u64 v[222:223], s[46:47], 0, v[0:1]
	s_mov_b32 m0, s22
	ds_read_b128 v[184:187], v178 offset:16384
	ds_read_b128 v[188:191], v178 offset:17408
	ds_read_b128 v[192:195], v178 offset:18432
	ds_read_b128 v[196:199], v178 offset:19456
	ds_read_b128 v[200:203], v178 offset:20480
	ds_read_b128 v[210:213], v178 offset:21504
	ds_read_b128 v[214:217], v178 offset:22528
	ds_read_b128 v[218:221], v178 offset:23552
	global_load_lds_dwordx4 v[222:223], off
	s_add_i32 m0, s22, 0x2000
	s_add_u32 s22, s46, 0x160000
	v_lshl_add_u64 v[224:225], s[46:47], 0, v[158:159]
	s_addc_u32 s23, s47, 0
	s_add_i32 s50, s51, s16
	global_load_lds_dwordx4 v[224:225], off
	s_mov_b32 m0, s50
	v_lshl_add_u64 v[228:229], s[48:49], 0, v[160:161]
	global_load_lds_dwordx4 v0, s[22:23]
	s_add_i32 m0, s50, 0x2000
	s_nop 0
	global_load_lds_dwordx4 v158, s[22:23]
	v_lshl_add_u64 v[226:227], s[48:49], 0, v[162:163]
	s_mov_b32 m0, s33
	s_nop 0
	global_load_lds_dwordx4 v[226:227], off
	s_mov_b32 m0, s37
	s_nop 0
	global_load_lds_dwordx4 v[228:229], off
	s_waitcnt vmcnt(8) lgkmcnt(0)
	s_barrier
	v_mfma_f32_16x16x32_bf16 v[78:81], v[42:45], v[184:187], v[78:81]
	v_mfma_f32_16x16x32_bf16 v[74:77], v[50:53], v[184:187], v[74:77]
	v_mfma_f32_16x16x32_bf16 v[62:65], v[42:45], v[192:195], v[62:65]
	v_mfma_f32_16x16x32_bf16 v[58:61], v[50:53], v[192:195], v[58:61]
	v_mfma_f32_16x16x32_bf16 v[30:33], v[42:45], v[200:203], v[30:33]
	v_mfma_f32_16x16x32_bf16 v[26:29], v[50:53], v[200:203], v[26:29]
	v_mfma_f32_16x16x32_bf16 v[14:17], v[42:45], v[214:217], v[14:17]
	v_mfma_f32_16x16x32_bf16 v[10:13], v[50:53], v[214:217], v[10:13]
	v_mfma_f32_16x16x32_bf16 v[78:81], v[46:49], v[188:191], v[78:81]
	v_mfma_f32_16x16x32_bf16 v[74:77], v[54:57], v[188:191], v[74:77]
	v_mfma_f32_16x16x32_bf16 v[62:65], v[46:49], v[196:199], v[62:65]
	v_mfma_f32_16x16x32_bf16 v[58:61], v[54:57], v[196:199], v[58:61]
	v_mfma_f32_16x16x32_bf16 v[30:33], v[46:49], v[210:213], v[30:33]
	v_mfma_f32_16x16x32_bf16 v[26:29], v[54:57], v[210:213], v[26:29]
	v_mfma_f32_16x16x32_bf16 v[14:17], v[46:49], v[218:221], v[14:17]
	v_mfma_f32_16x16x32_bf16 v[10:13], v[54:57], v[218:221], v[10:13]
	v_mfma_f32_16x16x32_bf16 v[38:41], v[154:157], v[192:195], v[38:41]
	v_mfma_f32_16x16x32_bf16 v[34:37], v[172:175], v[192:195], v[34:37]
	v_mfma_f32_16x16x32_bf16 v[22:25], v[154:157], v[200:203], v[22:25]
	v_mfma_f32_16x16x32_bf16 v[18:21], v[172:175], v[200:203], v[18:21]
	v_mfma_f32_16x16x32_bf16 v[6:9], v[154:157], v[214:217], v[6:9]
	v_mfma_f32_16x16x32_bf16 v[2:5], v[172:175], v[214:217], v[2:5]
	v_mfma_f32_16x16x32_bf16 v[42:45], v[154:157], v[184:187], v[70:73]
	v_mfma_f32_16x16x32_bf16 v[46:49], v[172:175], v[184:187], v[66:69]
	v_mfma_f32_16x16x32_bf16 v[38:41], v[168:171], v[196:199], v[38:41]
	v_mfma_f32_16x16x32_bf16 v[34:37], v[180:183], v[196:199], v[34:37]
	v_mfma_f32_16x16x32_bf16 v[22:25], v[168:171], v[210:213], v[22:25]
	v_mfma_f32_16x16x32_bf16 v[18:21], v[180:183], v[210:213], v[18:21]
	v_mfma_f32_16x16x32_bf16 v[6:9], v[168:171], v[218:221], v[6:9]
	v_mfma_f32_16x16x32_bf16 v[2:5], v[180:183], v[218:221], v[2:5]
	v_mfma_f32_16x16x32_bf16 v[42:45], v[168:171], v[188:191], v[42:45]
	v_mfma_f32_16x16x32_bf16 v[46:49], v[180:183], v[188:191], v[46:49]
	s_barrier
	s_add_i32 s50, 0, 0x18000
	s_add_i32 s51, 0, 0x1c000
	v_add_u32_e32 v70, s50, v176
	v_add_u32_e32 v179, s51, v176
	ds_read_b128 v[50:53], v70
	ds_read_b128 v[54:57], v70 offset:1024
	ds_read_b128 v[66:69], v70 offset:2048
	ds_read_b128 v[70:73], v70 offset:3072
	ds_read_b128 v[154:157], v179
	ds_read_b128 v[168:171], v179 offset:1024
	ds_read_b128 v[172:175], v179 offset:2048
	ds_read_b128 v[180:183], v179 offset:3072
	s_add_u32 s22, s48, 0x160000
	s_addc_u32 s23, s49, 0
	s_mov_b32 m0, s52
	ds_read_b128 v[184:187], v178 offset:32768
	ds_read_b128 v[188:191], v178 offset:33792
	ds_read_b128 v[192:195], v178 offset:34816
	ds_read_b128 v[196:199], v178 offset:35840
	ds_read_b128 v[200:203], v178 offset:36864
	ds_read_b128 v[210:213], v178 offset:37888
	ds_read_b128 v[214:217], v178 offset:38912
	ds_read_b128 v[218:221], v178 offset:39936
	global_load_lds_dwordx4 v162, s[22:23]
	s_mov_b32 m0, s53
	s_nop 0
	global_load_lds_dwordx4 v160, s[22:23]
	s_waitcnt vmcnt(8) lgkmcnt(0)
	s_barrier
	v_mfma_f32_16x16x32_bf16 v[142:145], v[50:53], v[184:187], v[142:145]
	v_mfma_f32_16x16x32_bf16 v[138:141], v[66:69], v[184:187], v[138:141]
	v_mfma_f32_16x16x32_bf16 v[126:129], v[50:53], v[192:195], v[126:129]
	v_mfma_f32_16x16x32_bf16 v[122:125], v[66:69], v[192:195], v[122:125]
	v_mfma_f32_16x16x32_bf16 v[110:113], v[50:53], v[200:203], v[110:113]
	v_mfma_f32_16x16x32_bf16 v[106:109], v[66:69], v[200:203], v[106:109]
	v_mfma_f32_16x16x32_bf16 v[94:97], v[50:53], v[214:217], v[94:97]
	v_mfma_f32_16x16x32_bf16 v[90:93], v[66:69], v[214:217], v[90:93]
	v_mfma_f32_16x16x32_bf16 v[142:145], v[54:57], v[188:191], v[142:145]
	v_mfma_f32_16x16x32_bf16 v[138:141], v[70:73], v[188:191], v[138:141]
	v_mfma_f32_16x16x32_bf16 v[126:129], v[54:57], v[196:199], v[126:129]
	v_mfma_f32_16x16x32_bf16 v[122:125], v[70:73], v[196:199], v[122:125]
	v_mfma_f32_16x16x32_bf16 v[110:113], v[54:57], v[210:213], v[110:113]
	v_mfma_f32_16x16x32_bf16 v[106:109], v[70:73], v[210:213], v[106:109]
	v_mfma_f32_16x16x32_bf16 v[94:97], v[54:57], v[218:221], v[94:97]
	v_mfma_f32_16x16x32_bf16 v[90:93], v[70:73], v[218:221], v[90:93]
	v_mfma_f32_16x16x32_bf16 v[134:137], v[154:157], v[184:187], v[134:137]
	v_mfma_f32_16x16x32_bf16 v[130:133], v[172:175], v[184:187], v[130:133]
	v_mfma_f32_16x16x32_bf16 v[118:121], v[154:157], v[192:195], v[118:121]
	v_mfma_f32_16x16x32_bf16 v[114:117], v[172:175], v[192:195], v[114:117]
	v_mfma_f32_16x16x32_bf16 v[102:105], v[154:157], v[200:203], v[102:105]
	v_mfma_f32_16x16x32_bf16 v[98:101], v[172:175], v[200:203], v[98:101]
	v_mfma_f32_16x16x32_bf16 v[86:89], v[154:157], v[214:217], v[86:89]
	v_mfma_f32_16x16x32_bf16 v[82:85], v[172:175], v[214:217], v[82:85]
	v_mfma_f32_16x16x32_bf16 v[134:137], v[168:171], v[188:191], v[134:137]
	v_mfma_f32_16x16x32_bf16 v[130:133], v[180:183], v[188:191], v[130:133]
	v_mfma_f32_16x16x32_bf16 v[118:121], v[168:171], v[196:199], v[118:121]
	v_mfma_f32_16x16x32_bf16 v[114:117], v[180:183], v[196:199], v[114:117]
	v_mfma_f32_16x16x32_bf16 v[102:105], v[168:171], v[210:213], v[102:105]
	v_mfma_f32_16x16x32_bf16 v[98:101], v[180:183], v[210:213], v[98:101]
	v_mfma_f32_16x16x32_bf16 v[86:89], v[168:171], v[218:221], v[86:89]
	v_mfma_f32_16x16x32_bf16 v[82:85], v[180:183], v[218:221], v[82:85]
	s_barrier
	s_add_i32 s22, s50, s16
	v_lshl_add_u64 v[222:223], v[222:223], 0, s[34:35]
	s_mov_b32 m0, s22
	ds_read_b128 v[184:187], v178 offset:49152
	ds_read_b128 v[188:191], v178 offset:50176
	ds_read_b128 v[192:195], v178 offset:51200
	ds_read_b128 v[196:199], v178 offset:52224
	ds_read_b128 v[200:203], v178 offset:53248
	ds_read_b128 v[210:213], v178 offset:54272
	ds_read_b128 v[214:217], v178 offset:55296
	ds_read_b128 v[218:221], v178 offset:56320
	global_load_lds_dwordx4 v[222:223], off
	s_add_i32 m0, s22, 0x2000
	s_add_u32 s22, s46, 0x160080
	v_lshl_add_u64 v[222:223], v[224:225], 0, s[34:35]
	s_addc_u32 s23, s47, 0
	s_add_i32 s46, s51, s16
	global_load_lds_dwordx4 v[222:223], off
	s_mov_b32 m0, s46
	s_nop 0
	global_load_lds_dwordx4 v0, s[22:23]
	s_add_i32 m0, s46, 0x2000
	s_nop 0
	global_load_lds_dwordx4 v158, s[22:23]
	v_lshl_add_u64 v[222:223], v[226:227], 0, s[34:35]
	s_mov_b32 m0, s55
	s_nop 0
	global_load_lds_dwordx4 v[222:223], off
	v_lshl_add_u64 v[222:223], v[228:229], 0, s[34:35]
	s_mov_b32 m0, s56
	s_nop 0
	global_load_lds_dwordx4 v[222:223], off
	s_waitcnt vmcnt(8) lgkmcnt(0)
	s_barrier
	v_mfma_f32_16x16x32_bf16 v[78:81], v[50:53], v[184:187], v[78:81]
	v_mfma_f32_16x16x32_bf16 v[74:77], v[66:69], v[184:187], v[74:77]
	v_mfma_f32_16x16x32_bf16 v[62:65], v[50:53], v[192:195], v[62:65]
	v_mfma_f32_16x16x32_bf16 v[58:61], v[66:69], v[192:195], v[58:61]
	v_mfma_f32_16x16x32_bf16 v[30:33], v[50:53], v[200:203], v[30:33]
	v_mfma_f32_16x16x32_bf16 v[26:29], v[66:69], v[200:203], v[26:29]
	v_mfma_f32_16x16x32_bf16 v[14:17], v[50:53], v[214:217], v[14:17]
	v_mfma_f32_16x16x32_bf16 v[10:13], v[66:69], v[214:217], v[10:13]
	v_mfma_f32_16x16x32_bf16 v[78:81], v[54:57], v[188:191], v[78:81]
	v_mfma_f32_16x16x32_bf16 v[74:77], v[70:73], v[188:191], v[74:77]
	v_mfma_f32_16x16x32_bf16 v[62:65], v[54:57], v[196:199], v[62:65]
	v_mfma_f32_16x16x32_bf16 v[58:61], v[70:73], v[196:199], v[58:61]
	v_mfma_f32_16x16x32_bf16 v[30:33], v[54:57], v[210:213], v[30:33]
	v_mfma_f32_16x16x32_bf16 v[26:29], v[70:73], v[210:213], v[26:29]
	v_mfma_f32_16x16x32_bf16 v[14:17], v[54:57], v[218:221], v[14:17]
	v_mfma_f32_16x16x32_bf16 v[10:13], v[70:73], v[218:221], v[10:13]
	v_mfma_f32_16x16x32_bf16 v[42:45], v[154:157], v[184:187], v[42:45]
	v_mfma_f32_16x16x32_bf16 v[70:73], v[168:171], v[188:191], v[42:45]
	v_mfma_f32_16x16x32_bf16 v[42:45], v[172:175], v[184:187], v[46:49]
	v_mfma_f32_16x16x32_bf16 v[38:41], v[154:157], v[192:195], v[38:41]
	v_mfma_f32_16x16x32_bf16 v[34:37], v[172:175], v[192:195], v[34:37]
	v_mfma_f32_16x16x32_bf16 v[22:25], v[154:157], v[200:203], v[22:25]
	v_mfma_f32_16x16x32_bf16 v[18:21], v[172:175], v[200:203], v[18:21]
	v_mfma_f32_16x16x32_bf16 v[6:9], v[154:157], v[214:217], v[6:9]
	v_mfma_f32_16x16x32_bf16 v[2:5], v[172:175], v[214:217], v[2:5]
	v_mfma_f32_16x16x32_bf16 v[66:69], v[180:183], v[188:191], v[42:45]
	v_mfma_f32_16x16x32_bf16 v[38:41], v[168:171], v[196:199], v[38:41]
	v_mfma_f32_16x16x32_bf16 v[34:37], v[180:183], v[196:199], v[34:37]
	v_mfma_f32_16x16x32_bf16 v[22:25], v[168:171], v[210:213], v[22:25]
	v_mfma_f32_16x16x32_bf16 v[18:21], v[180:183], v[210:213], v[18:21]
	v_mfma_f32_16x16x32_bf16 v[6:9], v[168:171], v[218:221], v[6:9]
	v_mfma_f32_16x16x32_bf16 v[2:5], v[180:183], v[218:221], v[2:5]
	s_barrier
	s_add_i32 s25, s25, 2
	s_add_u32 s18, s18, 0x100
	s_addc_u32 s19, s19, 0
	s_cmpk_gt_u32 s25, 0x55
	s_mov_b64 s[22:23], s[42:43]
	s_cbranch_scc0 .LBB0_728
	s_setprio 0
	s_and_b64 vcc, exec, s[12:13]
	s_cbranch_vccz .LBB0_731
	s_barrier
